# all five GEMM instances: first K iteration peeled with C=0 (no accumulator-zeroing v_mov); S5 pass-2 carry loads up front
# speedup vs baseline: 1.0332x; 1.0140x over previous
.LBB0_164:
	s_add_u32 s50, s16, 0x100
	s_addc_u32 s51, s17, 0
	s_mov_b32 s86, -2
	s_add_u32 s16, s14, 0x100
	s_addc_u32 s17, s15, 0
	s_add_i32 s22, 0, 0x10000
	s_cmp_eq_u32 s86, 8
	s_cselect_b32 s39, s11, s17
	s_cselect_b32 s38, s10, s16
	v_add_u32_e32 v142, s22, v145
	s_cselect_b32 s19, s13, s51
	s_cselect_b32 s18, s12, s50
	s_add_i32 s23, 0, 0x14000
	ds_read_b128 v[138:141], v142
	ds_read_b128 v[148:151], v142 offset:1024
	ds_read_b128 v[152:155], v142 offset:2048
	ds_read_b128 v[156:159], v142 offset:3072
	v_add_u32_e32 v142, s23, v145
	ds_read_b128 v[170:173], v142
	ds_read_b128 v[174:177], v142 offset:1024
	ds_read_b128 v[178:181], v142 offset:2048
	ds_read_b128 v[182:185], v142 offset:3072
	v_lshl_add_u64 v[142:143], s[14:15], 0, v[134:135]
	s_add_i32 m0, s41, 0xc000
	ds_read_b128 v[186:189], v147
	ds_read_b128 v[190:193], v147 offset:1024
	ds_read_b128 v[194:197], v147 offset:2048
	ds_read_b128 v[198:201], v147 offset:3072
	ds_read_b128 v[202:205], v147 offset:4096
	ds_read_b128 v[206:209], v147 offset:5120
	ds_read_b128 v[210:213], v147 offset:6144
	ds_read_b128 v[222:225], v147 offset:7168
	global_load_lds_dwordx4 v[142:143], off
	v_lshl_add_u64 v[142:143], s[14:15], 0, v[136:137]
	s_add_i32 m0, s41, 0xe000
	s_nop 0
	global_load_lds_dwordx4 v[142:143], off
	s_waitcnt vmcnt(8)
	s_waitcnt lgkmcnt(0)
	s_barrier
	s_setprio 1
	s_waitcnt lgkmcnt(0)
	v_mfma_f32_16x16x32_bf16 v[124:127], v[138:141], v[186:189], 0
	v_mfma_f32_16x16x32_bf16 v[120:123], v[152:155], v[186:189], 0
	v_mfma_f32_16x16x32_bf16 v[108:111], v[138:141], v[194:197], 0
	v_mfma_f32_16x16x32_bf16 v[104:107], v[152:155], v[194:197], 0
	v_mfma_f32_16x16x32_bf16 v[92:95], v[138:141], v[202:205], 0
	v_mfma_f32_16x16x32_bf16 v[88:91], v[152:155], v[202:205], 0
	v_mfma_f32_16x16x32_bf16 v[76:79], v[138:141], v[210:213], 0
	v_mfma_f32_16x16x32_bf16 v[72:75], v[152:155], v[210:213], 0
	v_mfma_f32_16x16x32_bf16 v[124:127], v[148:151], v[190:193], v[124:127]
	v_mfma_f32_16x16x32_bf16 v[120:123], v[156:159], v[190:193], v[120:123]
	v_mfma_f32_16x16x32_bf16 v[108:111], v[148:151], v[198:201], v[108:111]
	v_mfma_f32_16x16x32_bf16 v[104:107], v[156:159], v[198:201], v[104:107]
	v_mfma_f32_16x16x32_bf16 v[92:95], v[148:151], v[206:209], v[92:95]
	v_mfma_f32_16x16x32_bf16 v[88:91], v[156:159], v[206:209], v[88:91]
	v_mfma_f32_16x16x32_bf16 v[76:79], v[148:151], v[222:225], v[76:79]
	v_mfma_f32_16x16x32_bf16 v[72:75], v[156:159], v[222:225], v[72:75]
	s_setprio 0
	s_setprio 1
	v_mfma_f32_16x16x32_bf16 v[116:119], v[170:173], v[186:189], 0
	v_mfma_f32_16x16x32_bf16 v[112:115], v[178:181], v[186:189], 0
	v_mfma_f32_16x16x32_bf16 v[100:103], v[170:173], v[194:197], 0
	v_mfma_f32_16x16x32_bf16 v[96:99], v[178:181], v[194:197], 0
	v_mfma_f32_16x16x32_bf16 v[84:87], v[170:173], v[202:205], 0
	v_mfma_f32_16x16x32_bf16 v[80:83], v[178:181], v[202:205], 0
	v_mfma_f32_16x16x32_bf16 v[68:71], v[170:173], v[210:213], 0
	v_mfma_f32_16x16x32_bf16 v[64:67], v[178:181], v[210:213], 0
	v_mfma_f32_16x16x32_bf16 v[116:119], v[174:177], v[190:193], v[116:119]
	v_mfma_f32_16x16x32_bf16 v[112:115], v[182:185], v[190:193], v[112:115]
	v_mfma_f32_16x16x32_bf16 v[100:103], v[174:177], v[198:201], v[100:103]
	v_mfma_f32_16x16x32_bf16 v[96:99], v[182:185], v[198:201], v[96:99]
	v_mfma_f32_16x16x32_bf16 v[84:87], v[174:177], v[206:209], v[84:87]
	v_mfma_f32_16x16x32_bf16 v[80:83], v[182:185], v[206:209], v[80:83]
	v_mfma_f32_16x16x32_bf16 v[68:71], v[174:177], v[222:225], v[68:71]
	v_mfma_f32_16x16x32_bf16 v[64:67], v[182:185], v[222:225], v[64:67]
	s_setprio 0
	s_barrier
	s_add_i32 s14, s22, s27
	v_lshl_add_u64 v[142:143], s[18:19], 0, v[160:161]
	s_mov_b32 m0, s14
	ds_read_b128 v[186:189], v147 offset:16384
	ds_read_b128 v[190:193], v147 offset:17408
	ds_read_b128 v[194:197], v147 offset:18432
	ds_read_b128 v[198:201], v147 offset:19456
	ds_read_b128 v[202:205], v147 offset:20480
	ds_read_b128 v[206:209], v147 offset:21504
	ds_read_b128 v[210:213], v147 offset:22528
	ds_read_b128 v[222:225], v147 offset:23552
	global_load_lds_dwordx4 v[142:143], off
	s_add_i32 m0, s14, 0x2000
	s_add_u32 s14, s18, 0x30000
	v_lshl_add_u64 v[162:163], s[18:19], 0, v[128:129]
	s_addc_u32 s15, s19, 0
	s_add_i32 s22, s23, s27
	global_load_lds_dwordx4 v[162:163], off
	v_lshl_add_u64 v[164:165], s[14:15], 0, v[160:161]
	s_mov_b32 m0, s22
	v_lshl_add_u64 v[214:215], s[38:39], 0, v[130:131]
	global_load_lds_dwordx4 v[164:165], off
	v_lshl_add_u64 v[164:165], s[14:15], 0, v[128:129]
	s_add_i32 m0, s22, 0x2000
	s_nop 0
	global_load_lds_dwordx4 v[164:165], off
	v_lshl_add_u64 v[164:165], s[38:39], 0, v[132:133]
	s_mov_b32 m0, s41
	s_nop 0
	global_load_lds_dwordx4 v[164:165], off
	s_mov_b32 m0, s42
	s_nop 0
	global_load_lds_dwordx4 v[214:215], off
	s_waitcnt vmcnt(8)
	s_waitcnt lgkmcnt(0)
	s_barrier
	s_setprio 1
	s_waitcnt lgkmcnt(0)
	v_mfma_f32_16x16x32_bf16 v[60:63], v[138:141], v[186:189], 0
	v_mfma_f32_16x16x32_bf16 v[56:59], v[152:155], v[186:189], 0
	v_mfma_f32_16x16x32_bf16 v[44:47], v[138:141], v[194:197], 0
	v_mfma_f32_16x16x32_bf16 v[40:43], v[152:155], v[194:197], 0
	v_mfma_f32_16x16x32_bf16 v[28:31], v[138:141], v[202:205], 0
	v_mfma_f32_16x16x32_bf16 v[24:27], v[152:155], v[202:205], 0
	v_mfma_f32_16x16x32_bf16 v[12:15], v[138:141], v[210:213], 0
	v_mfma_f32_16x16x32_bf16 v[8:11], v[152:155], v[210:213], 0
	v_mfma_f32_16x16x32_bf16 v[60:63], v[148:151], v[190:193], v[60:63]
	v_mfma_f32_16x16x32_bf16 v[56:59], v[156:159], v[190:193], v[56:59]
	v_mfma_f32_16x16x32_bf16 v[44:47], v[148:151], v[198:201], v[44:47]
	v_mfma_f32_16x16x32_bf16 v[40:43], v[156:159], v[198:201], v[40:43]
	v_mfma_f32_16x16x32_bf16 v[28:31], v[148:151], v[206:209], v[28:31]
	v_mfma_f32_16x16x32_bf16 v[24:27], v[156:159], v[206:209], v[24:27]
	v_mfma_f32_16x16x32_bf16 v[12:15], v[148:151], v[222:225], v[12:15]
	v_mfma_f32_16x16x32_bf16 v[8:11], v[156:159], v[222:225], v[8:11]
	s_setprio 0
	s_setprio 1
	v_mfma_f32_16x16x32_bf16 v[52:55], v[170:173], v[186:189], 0
	v_mfma_f32_16x16x32_bf16 v[48:51], v[178:181], v[186:189], 0
	v_mfma_f32_16x16x32_bf16 v[36:39], v[170:173], v[194:197], 0
	v_mfma_f32_16x16x32_bf16 v[32:35], v[178:181], v[194:197], 0
	v_mfma_f32_16x16x32_bf16 v[20:23], v[170:173], v[202:205], 0
	v_mfma_f32_16x16x32_bf16 v[16:19], v[178:181], v[202:205], 0
	v_mfma_f32_16x16x32_bf16 v[4:7], v[170:173], v[210:213], 0
	v_mfma_f32_16x16x32_bf16 v[0:3], v[178:181], v[210:213], 0
	v_mfma_f32_16x16x32_bf16 v[52:55], v[174:177], v[190:193], v[52:55]
	v_mfma_f32_16x16x32_bf16 v[48:51], v[182:185], v[190:193], v[48:51]
	v_mfma_f32_16x16x32_bf16 v[36:39], v[174:177], v[198:201], v[36:39]
	v_mfma_f32_16x16x32_bf16 v[32:35], v[182:185], v[198:201], v[32:35]
	v_mfma_f32_16x16x32_bf16 v[20:23], v[174:177], v[206:209], v[20:23]
	v_mfma_f32_16x16x32_bf16 v[16:19], v[182:185], v[206:209], v[16:19]
	v_mfma_f32_16x16x32_bf16 v[4:7], v[174:177], v[222:225], v[4:7]
	v_mfma_f32_16x16x32_bf16 v[0:3], v[182:185], v[222:225], v[0:3]
	s_setprio 0
	s_barrier
	s_add_i32 s22, 0, 0x18000
	s_add_i32 s23, 0, 0x1c000
	v_add_u32_e32 v156, s22, v145
	v_add_u32_e32 v167, s23, v145
	ds_read_b128 v[138:141], v156
	ds_read_b128 v[148:151], v156 offset:1024
	ds_read_b128 v[152:155], v156 offset:2048
	ds_read_b128 v[156:159], v156 offset:3072
	ds_read_b128 v[170:173], v167
	ds_read_b128 v[174:177], v167 offset:1024
	ds_read_b128 v[178:181], v167 offset:2048
	ds_read_b128 v[182:185], v167 offset:3072
	s_add_u32 s14, s38, 0x30000
	s_addc_u32 s15, s39, 0
	s_mov_b32 m0, s43
	v_lshl_add_u64 v[226:227], s[14:15], 0, v[132:133]
	ds_read_b128 v[186:189], v147 offset:32768
	ds_read_b128 v[190:193], v147 offset:33792
	ds_read_b128 v[194:197], v147 offset:34816
	ds_read_b128 v[198:201], v147 offset:35840
	ds_read_b128 v[202:205], v147 offset:36864
	ds_read_b128 v[206:209], v147 offset:37888
	ds_read_b128 v[210:213], v147 offset:38912
	ds_read_b128 v[222:225], v147 offset:39936
	global_load_lds_dwordx4 v[226:227], off
	v_lshl_add_u64 v[226:227], s[14:15], 0, v[130:131]
	s_mov_b32 m0, s80
	s_nop 0
	global_load_lds_dwordx4 v[226:227], off
	s_waitcnt vmcnt(8)
	s_waitcnt lgkmcnt(0)
	s_barrier
	s_setprio 1
	s_waitcnt lgkmcnt(0)
	v_mfma_f32_16x16x32_bf16 v[124:127], v[138:141], v[186:189], v[124:127]
	v_mfma_f32_16x16x32_bf16 v[120:123], v[152:155], v[186:189], v[120:123]
	v_mfma_f32_16x16x32_bf16 v[108:111], v[138:141], v[194:197], v[108:111]
	v_mfma_f32_16x16x32_bf16 v[104:107], v[152:155], v[194:197], v[104:107]
	v_mfma_f32_16x16x32_bf16 v[92:95], v[138:141], v[202:205], v[92:95]
	v_mfma_f32_16x16x32_bf16 v[88:91], v[152:155], v[202:205], v[88:91]
	v_mfma_f32_16x16x32_bf16 v[76:79], v[138:141], v[210:213], v[76:79]
	v_mfma_f32_16x16x32_bf16 v[72:75], v[152:155], v[210:213], v[72:75]
	v_mfma_f32_16x16x32_bf16 v[124:127], v[148:151], v[190:193], v[124:127]
	v_mfma_f32_16x16x32_bf16 v[120:123], v[156:159], v[190:193], v[120:123]
	v_mfma_f32_16x16x32_bf16 v[108:111], v[148:151], v[198:201], v[108:111]
	v_mfma_f32_16x16x32_bf16 v[104:107], v[156:159], v[198:201], v[104:107]
	v_mfma_f32_16x16x32_bf16 v[92:95], v[148:151], v[206:209], v[92:95]
	v_mfma_f32_16x16x32_bf16 v[88:91], v[156:159], v[206:209], v[88:91]
	v_mfma_f32_16x16x32_bf16 v[76:79], v[148:151], v[222:225], v[76:79]
	v_mfma_f32_16x16x32_bf16 v[72:75], v[156:159], v[222:225], v[72:75]
	s_setprio 0
	s_setprio 1
	v_mfma_f32_16x16x32_bf16 v[116:119], v[170:173], v[186:189], v[116:119]
	v_mfma_f32_16x16x32_bf16 v[112:115], v[178:181], v[186:189], v[112:115]
	v_mfma_f32_16x16x32_bf16 v[100:103], v[170:173], v[194:197], v[100:103]
	v_mfma_f32_16x16x32_bf16 v[96:99], v[178:181], v[194:197], v[96:99]
	v_mfma_f32_16x16x32_bf16 v[84:87], v[170:173], v[202:205], v[84:87]
	v_mfma_f32_16x16x32_bf16 v[80:83], v[178:181], v[202:205], v[80:83]
	v_mfma_f32_16x16x32_bf16 v[68:71], v[170:173], v[210:213], v[68:71]
	v_mfma_f32_16x16x32_bf16 v[64:67], v[178:181], v[210:213], v[64:67]
	v_mfma_f32_16x16x32_bf16 v[116:119], v[174:177], v[190:193], v[116:119]
	v_mfma_f32_16x16x32_bf16 v[112:115], v[182:185], v[190:193], v[112:115]
	v_mfma_f32_16x16x32_bf16 v[100:103], v[174:177], v[198:201], v[100:103]
	v_mfma_f32_16x16x32_bf16 v[96:99], v[182:185], v[198:201], v[96:99]
	v_mfma_f32_16x16x32_bf16 v[84:87], v[174:177], v[206:209], v[84:87]
	v_mfma_f32_16x16x32_bf16 v[80:83], v[182:185], v[206:209], v[80:83]
	v_mfma_f32_16x16x32_bf16 v[68:71], v[174:177], v[222:225], v[68:71]
	v_mfma_f32_16x16x32_bf16 v[64:67], v[182:185], v[222:225], v[64:67]
	s_setprio 0
	s_barrier
	s_add_i32 s14, s22, s27
	v_lshl_add_u64 v[142:143], v[142:143], 0, s[48:49]
	s_mov_b32 m0, s14
	ds_read_b128 v[186:189], v147 offset:49152
	ds_read_b128 v[190:193], v147 offset:50176
	ds_read_b128 v[194:197], v147 offset:51200
	ds_read_b128 v[198:201], v147 offset:52224
	ds_read_b128 v[202:205], v147 offset:53248
	ds_read_b128 v[206:209], v147 offset:54272
	ds_read_b128 v[210:213], v147 offset:55296
	ds_read_b128 v[222:225], v147 offset:56320
	global_load_lds_dwordx4 v[142:143], off
	s_add_i32 m0, s14, 0x2000
	s_add_u32 s14, s18, 0x30080
	v_lshl_add_u64 v[142:143], v[162:163], 0, s[48:49]
	s_addc_u32 s15, s19, 0
	s_add_i32 s18, s23, s27
	global_load_lds_dwordx4 v[142:143], off
	v_lshl_add_u64 v[142:143], s[14:15], 0, v[160:161]
	s_mov_b32 m0, s18
	s_nop 0
	global_load_lds_dwordx4 v[142:143], off
	v_lshl_add_u64 v[142:143], s[14:15], 0, v[128:129]
	s_add_i32 m0, s18, 0x2000
	s_nop 0
	global_load_lds_dwordx4 v[142:143], off
	v_lshl_add_u64 v[142:143], v[164:165], 0, s[48:49]
	s_mov_b32 m0, s81
	s_nop 0
	global_load_lds_dwordx4 v[142:143], off
	v_lshl_add_u64 v[142:143], v[214:215], 0, s[48:49]
	s_mov_b32 m0, s82
	s_nop 0
	global_load_lds_dwordx4 v[142:143], off
	s_waitcnt vmcnt(8)
	s_waitcnt lgkmcnt(0)
	s_barrier
	s_setprio 1
	s_waitcnt lgkmcnt(0)
	v_mfma_f32_16x16x32_bf16 v[60:63], v[138:141], v[186:189], v[60:63]
	v_mfma_f32_16x16x32_bf16 v[56:59], v[152:155], v[186:189], v[56:59]
	v_mfma_f32_16x16x32_bf16 v[44:47], v[138:141], v[194:197], v[44:47]
	v_mfma_f32_16x16x32_bf16 v[40:43], v[152:155], v[194:197], v[40:43]
	v_mfma_f32_16x16x32_bf16 v[28:31], v[138:141], v[202:205], v[28:31]
	v_mfma_f32_16x16x32_bf16 v[24:27], v[152:155], v[202:205], v[24:27]
	v_mfma_f32_16x16x32_bf16 v[12:15], v[138:141], v[210:213], v[12:15]
	v_mfma_f32_16x16x32_bf16 v[8:11], v[152:155], v[210:213], v[8:11]
	v_mfma_f32_16x16x32_bf16 v[60:63], v[148:151], v[190:193], v[60:63]
	v_mfma_f32_16x16x32_bf16 v[56:59], v[156:159], v[190:193], v[56:59]
	v_mfma_f32_16x16x32_bf16 v[44:47], v[148:151], v[198:201], v[44:47]
	v_mfma_f32_16x16x32_bf16 v[40:43], v[156:159], v[198:201], v[40:43]
	v_mfma_f32_16x16x32_bf16 v[28:31], v[148:151], v[206:209], v[28:31]
	v_mfma_f32_16x16x32_bf16 v[24:27], v[156:159], v[206:209], v[24:27]
	v_mfma_f32_16x16x32_bf16 v[12:15], v[148:151], v[222:225], v[12:15]
	v_mfma_f32_16x16x32_bf16 v[8:11], v[156:159], v[222:225], v[8:11]
	s_setprio 0
	s_setprio 1
	v_mfma_f32_16x16x32_bf16 v[52:55], v[170:173], v[186:189], v[52:55]
	v_mfma_f32_16x16x32_bf16 v[48:51], v[178:181], v[186:189], v[48:51]
	v_mfma_f32_16x16x32_bf16 v[36:39], v[170:173], v[194:197], v[36:39]
	v_mfma_f32_16x16x32_bf16 v[32:35], v[178:181], v[194:197], v[32:35]
	v_mfma_f32_16x16x32_bf16 v[20:23], v[170:173], v[202:205], v[20:23]
	v_mfma_f32_16x16x32_bf16 v[16:19], v[178:181], v[202:205], v[16:19]
	v_mfma_f32_16x16x32_bf16 v[4:7], v[170:173], v[210:213], v[4:7]
	v_mfma_f32_16x16x32_bf16 v[0:3], v[178:181], v[210:213], v[0:3]
	v_mfma_f32_16x16x32_bf16 v[52:55], v[174:177], v[190:193], v[52:55]
	v_mfma_f32_16x16x32_bf16 v[48:51], v[182:185], v[190:193], v[48:51]
	v_mfma_f32_16x16x32_bf16 v[36:39], v[174:177], v[198:201], v[36:39]
	v_mfma_f32_16x16x32_bf16 v[32:35], v[182:185], v[198:201], v[32:35]
	v_mfma_f32_16x16x32_bf16 v[20:23], v[174:177], v[206:209], v[20:23]
	v_mfma_f32_16x16x32_bf16 v[16:19], v[182:185], v[206:209], v[16:19]
	v_mfma_f32_16x16x32_bf16 v[4:7], v[174:177], v[222:225], v[4:7]
	v_mfma_f32_16x16x32_bf16 v[0:3], v[182:185], v[222:225], v[0:3]
	s_setprio 0
	s_barrier
	s_add_i32 s86, s86, 2
	s_add_u32 s50, s50, 0x100
	s_addc_u32 s51, s51, 0
	s_cmp_gt_u32 s86, 9
	s_mov_b64 s[14:15], s[16:17]

.LBB0_252:
	s_ashr_i32 s19, s18, 31
	s_lshl_b64 s[6:7], s[18:19], 19
	s_add_u32 s84, s0, s6
	s_addc_u32 s85, s1, s7
	s_and_b64 s[6:7], s[38:39], exec
	s_cselect_b32 s4, s85, s43
	s_cselect_b32 s11, s84, s42
	s_ashr_i32 s17, s16, 31
	s_lshl_b64 s[6:7], s[16:17], 19
	s_add_u32 s6, s26, s6
	s_addc_u32 s7, s27, s7
	s_and_b64 s[24:25], s[38:39], exec
	s_cselect_b32 s17, s7, s83
	s_cselect_b32 s19, s6, s82
	s_add_u32 s42, s42, 0x40080
	s_addc_u32 s43, s43, 0
	s_add_u32 s24, s82, 0x100
	s_addc_u32 s25, s83, 0
	s_mov_b32 s41, -2
	s_waitcnt lgkmcnt(0)
	s_add_u32 s22, s42, 0xfffc0080
	s_addc_u32 s23, s43, -1
	s_add_i32 s28, 0, 0x10000
	s_cmp_eq_u32 s41, 12
	s_cselect_b32 vcc_hi, s4, s23
	s_cselect_b32 vcc_lo, s11, s22
	v_add_u32_e32 v160, s28, v167
	s_cselect_b32 s83, s17, s25
	s_cselect_b32 s82, s19, s24
	s_add_i32 s22, 0, 0x14000
	ds_read_b128 v[148:151], v160
	ds_read_b128 v[152:155], v160 offset:1024
	ds_read_b128 v[156:159], v160 offset:2048
	ds_read_b128 v[174:177], v160 offset:3072
	v_add_u32_e32 v160, s22, v167
	ds_read_b128 v[178:181], v160
	ds_read_b128 v[182:185], v160 offset:1024
	ds_read_b128 v[186:189], v160 offset:2048
	ds_read_b128 v[190:193], v160 offset:3072
	v_lshl_add_u64 v[162:163], s[42:43], 0, v[144:145]
	s_add_i32 m0, s81, 0xc000
	ds_read_b128 v[194:197], v173
	ds_read_b128 v[198:201], v173 offset:1024
	ds_read_b128 v[202:205], v173 offset:2048
	ds_read_b128 v[206:209], v173 offset:3072
	ds_read_b128 v[210:213], v173 offset:4096
	ds_read_b128 v[222:225], v173 offset:5120
	ds_read_b128 v[234:237], v173 offset:6144
	ds_read_b128 v[238:241], v173 offset:7168
	global_load_lds_dwordx4 v[162:163], off
	v_lshl_add_u64 v[162:163], s[42:43], 0, v[146:147]
	s_add_i32 m0, s81, 0xe000
	s_nop 0
	global_load_lds_dwordx4 v[162:163], off
	s_waitcnt vmcnt(8)
	s_waitcnt lgkmcnt(0)
	s_barrier
	s_setprio 1
	s_waitcnt lgkmcnt(0)
	v_mfma_f32_16x16x32_bf16 v[124:127], v[148:151], v[194:197], 0
	v_mfma_f32_16x16x32_bf16 v[120:123], v[156:159], v[194:197], 0
	v_mfma_f32_16x16x32_bf16 v[108:111], v[148:151], v[202:205], 0
	v_mfma_f32_16x16x32_bf16 v[104:107], v[156:159], v[202:205], 0
	v_mfma_f32_16x16x32_bf16 v[92:95], v[148:151], v[210:213], 0
	v_mfma_f32_16x16x32_bf16 v[88:91], v[156:159], v[210:213], 0
	v_mfma_f32_16x16x32_bf16 v[76:79], v[148:151], v[234:237], 0
	v_mfma_f32_16x16x32_bf16 v[72:75], v[156:159], v[234:237], 0
	v_mfma_f32_16x16x32_bf16 v[124:127], v[152:155], v[198:201], v[124:127]
	v_mfma_f32_16x16x32_bf16 v[120:123], v[174:177], v[198:201], v[120:123]
	v_mfma_f32_16x16x32_bf16 v[108:111], v[152:155], v[206:209], v[108:111]
	v_mfma_f32_16x16x32_bf16 v[104:107], v[174:177], v[206:209], v[104:107]
	v_mfma_f32_16x16x32_bf16 v[92:95], v[152:155], v[222:225], v[92:95]
	v_mfma_f32_16x16x32_bf16 v[88:91], v[174:177], v[222:225], v[88:91]
	v_mfma_f32_16x16x32_bf16 v[76:79], v[152:155], v[238:241], v[76:79]
	v_mfma_f32_16x16x32_bf16 v[72:75], v[174:177], v[238:241], v[72:75]
	s_setprio 0
	s_setprio 1
	v_mfma_f32_16x16x32_bf16 v[116:119], v[178:181], v[194:197], 0
	v_mfma_f32_16x16x32_bf16 v[112:115], v[186:189], v[194:197], 0
	v_mfma_f32_16x16x32_bf16 v[100:103], v[178:181], v[202:205], 0
	v_mfma_f32_16x16x32_bf16 v[96:99], v[186:189], v[202:205], 0
	v_mfma_f32_16x16x32_bf16 v[84:87], v[178:181], v[210:213], 0
	v_mfma_f32_16x16x32_bf16 v[80:83], v[186:189], v[210:213], 0
	v_mfma_f32_16x16x32_bf16 v[68:71], v[178:181], v[234:237], 0
	v_mfma_f32_16x16x32_bf16 v[64:67], v[186:189], v[234:237], 0
	v_mfma_f32_16x16x32_bf16 v[116:119], v[182:185], v[198:201], v[116:119]
	v_mfma_f32_16x16x32_bf16 v[112:115], v[190:193], v[198:201], v[112:115]
	v_mfma_f32_16x16x32_bf16 v[100:103], v[182:185], v[206:209], v[100:103]
	v_mfma_f32_16x16x32_bf16 v[96:99], v[190:193], v[206:209], v[96:99]
	v_mfma_f32_16x16x32_bf16 v[84:87], v[182:185], v[222:225], v[84:87]
	v_mfma_f32_16x16x32_bf16 v[80:83], v[190:193], v[222:225], v[80:83]
	v_mfma_f32_16x16x32_bf16 v[68:71], v[182:185], v[238:241], v[68:71]
	v_mfma_f32_16x16x32_bf16 v[64:67], v[190:193], v[238:241], v[64:67]
	s_setprio 0
	s_barrier
	s_add_i32 s23, s28, s80
	v_lshl_add_u64 v[162:163], s[82:83], 0, v[130:131]
	s_mov_b32 m0, s23
	ds_read_b128 v[194:197], v173 offset:16384
	ds_read_b128 v[198:201], v173 offset:17408
	ds_read_b128 v[202:205], v173 offset:18432
	ds_read_b128 v[206:209], v173 offset:19456
	ds_read_b128 v[210:213], v173 offset:20480
	ds_read_b128 v[222:225], v173 offset:21504
	ds_read_b128 v[234:237], v173 offset:22528
	ds_read_b128 v[238:241], v173 offset:23552
	global_load_lds_dwordx4 v[162:163], off
	s_add_i32 m0, s23, 0x2000
	s_add_u32 s50, s82, 0x40000
	v_lshl_add_u64 v[164:165], s[82:83], 0, v[134:135]
	s_addc_u32 s51, s83, 0
	s_add_i32 s22, s22, s80
	global_load_lds_dwordx4 v[164:165], off
	v_lshl_add_u64 v[170:171], s[50:51], 0, v[130:131]
	s_mov_b32 m0, s22
	v_lshl_add_u64 v[214:215], vcc, 0, v[132:133]
	global_load_lds_dwordx4 v[170:171], off
	v_lshl_add_u64 v[170:171], s[50:51], 0, v[134:135]
	s_add_i32 m0, s22, 0x2000
	s_nop 0
	global_load_lds_dwordx4 v[170:171], off
	v_lshl_add_u64 v[170:171], vcc, 0, v[128:129]
	s_mov_b32 m0, s81
	s_nop 0
	global_load_lds_dwordx4 v[170:171], off
	s_mov_b32 m0, s86
	s_nop 0
	global_load_lds_dwordx4 v[214:215], off
	s_waitcnt vmcnt(8)
	s_waitcnt lgkmcnt(0)
	s_barrier
	s_setprio 1
	s_waitcnt lgkmcnt(0)
	v_mfma_f32_16x16x32_bf16 v[60:63], v[148:151], v[194:197], 0
	v_mfma_f32_16x16x32_bf16 v[56:59], v[156:159], v[194:197], 0
	v_mfma_f32_16x16x32_bf16 v[44:47], v[148:151], v[202:205], 0
	v_mfma_f32_16x16x32_bf16 v[40:43], v[156:159], v[202:205], 0
	v_mfma_f32_16x16x32_bf16 v[28:31], v[148:151], v[210:213], 0
	v_mfma_f32_16x16x32_bf16 v[24:27], v[156:159], v[210:213], 0
	v_mfma_f32_16x16x32_bf16 v[12:15], v[148:151], v[234:237], 0
	v_mfma_f32_16x16x32_bf16 v[8:11], v[156:159], v[234:237], 0
	v_mfma_f32_16x16x32_bf16 v[60:63], v[152:155], v[198:201], v[60:63]
	v_mfma_f32_16x16x32_bf16 v[56:59], v[174:177], v[198:201], v[56:59]
	v_mfma_f32_16x16x32_bf16 v[44:47], v[152:155], v[206:209], v[44:47]
	v_mfma_f32_16x16x32_bf16 v[40:43], v[174:177], v[206:209], v[40:43]
	v_mfma_f32_16x16x32_bf16 v[28:31], v[152:155], v[222:225], v[28:31]
	v_mfma_f32_16x16x32_bf16 v[24:27], v[174:177], v[222:225], v[24:27]
	v_mfma_f32_16x16x32_bf16 v[12:15], v[152:155], v[238:241], v[12:15]
	v_mfma_f32_16x16x32_bf16 v[8:11], v[174:177], v[238:241], v[8:11]
	s_setprio 0
	s_setprio 1
	v_mfma_f32_16x16x32_bf16 v[52:55], v[178:181], v[194:197], 0
	v_mfma_f32_16x16x32_bf16 v[48:51], v[186:189], v[194:197], 0
	v_mfma_f32_16x16x32_bf16 v[36:39], v[178:181], v[202:205], 0
	v_mfma_f32_16x16x32_bf16 v[32:35], v[186:189], v[202:205], 0
	v_mfma_f32_16x16x32_bf16 v[20:23], v[178:181], v[210:213], 0
	v_mfma_f32_16x16x32_bf16 v[16:19], v[186:189], v[210:213], 0
	v_mfma_f32_16x16x32_bf16 v[4:7], v[178:181], v[234:237], 0
	v_mfma_f32_16x16x32_bf16 v[0:3], v[186:189], v[234:237], 0
	v_mfma_f32_16x16x32_bf16 v[52:55], v[182:185], v[198:201], v[52:55]
	v_mfma_f32_16x16x32_bf16 v[48:51], v[190:193], v[198:201], v[48:51]
	v_mfma_f32_16x16x32_bf16 v[36:39], v[182:185], v[206:209], v[36:39]
	v_mfma_f32_16x16x32_bf16 v[32:35], v[190:193], v[206:209], v[32:35]
	v_mfma_f32_16x16x32_bf16 v[20:23], v[182:185], v[222:225], v[20:23]
	v_mfma_f32_16x16x32_bf16 v[16:19], v[190:193], v[222:225], v[16:19]
	v_mfma_f32_16x16x32_bf16 v[4:7], v[182:185], v[238:241], v[4:7]
	v_mfma_f32_16x16x32_bf16 v[0:3], v[190:193], v[238:241], v[0:3]
	s_setprio 0
	s_barrier
	s_add_i32 s22, 0, 0x18000
	v_add_u32_e32 v160, s22, v167
	s_add_i32 s23, 0, 0x1c000
	ds_read_b128 v[148:151], v160
	ds_read_b128 v[152:155], v160 offset:1024
	ds_read_b128 v[156:159], v160 offset:2048
	ds_read_b128 v[174:177], v160 offset:3072
	v_add_u32_e32 v160, s23, v167
	ds_read_b128 v[178:181], v160
	ds_read_b128 v[182:185], v160 offset:1024
	ds_read_b128 v[186:189], v160 offset:2048
	ds_read_b128 v[190:193], v160 offset:3072
	s_add_u32 s50, vcc_lo, 0x40000
	s_addc_u32 s51, vcc_hi, 0
	s_mov_b32 m0, s87
	v_lshl_add_u64 v[226:227], s[50:51], 0, v[128:129]
	ds_read_b128 v[194:197], v173 offset:32768
	ds_read_b128 v[198:201], v173 offset:33792
	ds_read_b128 v[202:205], v173 offset:34816
	ds_read_b128 v[206:209], v173 offset:35840
	ds_read_b128 v[210:213], v173 offset:36864
	ds_read_b128 v[222:225], v173 offset:37888
	ds_read_b128 v[234:237], v173 offset:38912
	ds_read_b128 v[238:241], v173 offset:39936
	global_load_lds_dwordx4 v[226:227], off
	v_lshl_add_u64 v[226:227], s[50:51], 0, v[132:133]
	s_mov_b32 m0, s88
	s_nop 0
	global_load_lds_dwordx4 v[226:227], off
	s_waitcnt vmcnt(8)
	s_waitcnt lgkmcnt(0)
	s_barrier
	s_setprio 1
	s_waitcnt lgkmcnt(0)
	v_mfma_f32_16x16x32_bf16 v[124:127], v[148:151], v[194:197], v[124:127]
	v_mfma_f32_16x16x32_bf16 v[120:123], v[156:159], v[194:197], v[120:123]
	v_mfma_f32_16x16x32_bf16 v[108:111], v[148:151], v[202:205], v[108:111]
	v_mfma_f32_16x16x32_bf16 v[104:107], v[156:159], v[202:205], v[104:107]
	v_mfma_f32_16x16x32_bf16 v[92:95], v[148:151], v[210:213], v[92:95]
	v_mfma_f32_16x16x32_bf16 v[88:91], v[156:159], v[210:213], v[88:91]
	v_mfma_f32_16x16x32_bf16 v[76:79], v[148:151], v[234:237], v[76:79]
	v_mfma_f32_16x16x32_bf16 v[72:75], v[156:159], v[234:237], v[72:75]
	v_mfma_f32_16x16x32_bf16 v[124:127], v[152:155], v[198:201], v[124:127]
	v_mfma_f32_16x16x32_bf16 v[120:123], v[174:177], v[198:201], v[120:123]
	v_mfma_f32_16x16x32_bf16 v[108:111], v[152:155], v[206:209], v[108:111]
	v_mfma_f32_16x16x32_bf16 v[104:107], v[174:177], v[206:209], v[104:107]
	v_mfma_f32_16x16x32_bf16 v[92:95], v[152:155], v[222:225], v[92:95]
	v_mfma_f32_16x16x32_bf16 v[88:91], v[174:177], v[222:225], v[88:91]
	v_mfma_f32_16x16x32_bf16 v[76:79], v[152:155], v[238:241], v[76:79]
	v_mfma_f32_16x16x32_bf16 v[72:75], v[174:177], v[238:241], v[72:75]
	s_setprio 0
	s_setprio 1
	v_mfma_f32_16x16x32_bf16 v[116:119], v[178:181], v[194:197], v[116:119]
	v_mfma_f32_16x16x32_bf16 v[112:115], v[186:189], v[194:197], v[112:115]
	v_mfma_f32_16x16x32_bf16 v[100:103], v[178:181], v[202:205], v[100:103]
	v_mfma_f32_16x16x32_bf16 v[96:99], v[186:189], v[202:205], v[96:99]
	v_mfma_f32_16x16x32_bf16 v[84:87], v[178:181], v[210:213], v[84:87]
	v_mfma_f32_16x16x32_bf16 v[80:83], v[186:189], v[210:213], v[80:83]
	v_mfma_f32_16x16x32_bf16 v[68:71], v[178:181], v[234:237], v[68:71]
	v_mfma_f32_16x16x32_bf16 v[64:67], v[186:189], v[234:237], v[64:67]
	v_mfma_f32_16x16x32_bf16 v[116:119], v[182:185], v[198:201], v[116:119]
	v_mfma_f32_16x16x32_bf16 v[112:115], v[190:193], v[198:201], v[112:115]
	v_mfma_f32_16x16x32_bf16 v[100:103], v[182:185], v[206:209], v[100:103]
	v_mfma_f32_16x16x32_bf16 v[96:99], v[190:193], v[206:209], v[96:99]
	v_mfma_f32_16x16x32_bf16 v[84:87], v[182:185], v[222:225], v[84:87]
	v_mfma_f32_16x16x32_bf16 v[80:83], v[190:193], v[222:225], v[80:83]
	v_mfma_f32_16x16x32_bf16 v[68:71], v[182:185], v[238:241], v[68:71]
	v_mfma_f32_16x16x32_bf16 v[64:67], v[190:193], v[238:241], v[64:67]
	s_setprio 0
	s_barrier
	s_add_i32 s22, s22, s80
	v_lshl_add_u64 v[162:163], v[162:163], 0, s[48:49]
	s_mov_b32 m0, s22
	ds_read_b128 v[194:197], v173 offset:49152
	ds_read_b128 v[198:201], v173 offset:50176
	ds_read_b128 v[202:205], v173 offset:51200
	ds_read_b128 v[206:209], v173 offset:52224
	ds_read_b128 v[210:213], v173 offset:53248
	ds_read_b128 v[222:225], v173 offset:54272
	ds_read_b128 v[234:237], v173 offset:55296
	ds_read_b128 v[238:241], v173 offset:56320
	global_load_lds_dwordx4 v[162:163], off
	s_add_i32 m0, s22, 0x2000
	s_add_u32 s50, s82, 0x40080
	v_lshl_add_u64 v[162:163], v[164:165], 0, s[48:49]
	s_addc_u32 s51, s83, 0
	s_add_i32 s22, s23, s80
	global_load_lds_dwordx4 v[162:163], off
	v_lshl_add_u64 v[162:163], s[50:51], 0, v[130:131]
	s_mov_b32 m0, s22
	s_nop 0
	global_load_lds_dwordx4 v[162:163], off
	v_lshl_add_u64 v[162:163], s[50:51], 0, v[134:135]
	s_add_i32 m0, s22, 0x2000
	s_nop 0
	global_load_lds_dwordx4 v[162:163], off
	v_lshl_add_u64 v[162:163], v[170:171], 0, s[48:49]
	s_mov_b32 m0, s90
	s_nop 0
	global_load_lds_dwordx4 v[162:163], off
	v_lshl_add_u64 v[162:163], v[214:215], 0, s[48:49]
	s_mov_b32 m0, s91
	s_nop 0
	global_load_lds_dwordx4 v[162:163], off
	s_waitcnt vmcnt(8)
	s_waitcnt lgkmcnt(0)
	s_barrier
	s_setprio 1
	s_waitcnt lgkmcnt(0)
	v_mfma_f32_16x16x32_bf16 v[60:63], v[148:151], v[194:197], v[60:63]
	v_mfma_f32_16x16x32_bf16 v[56:59], v[156:159], v[194:197], v[56:59]
	v_mfma_f32_16x16x32_bf16 v[44:47], v[148:151], v[202:205], v[44:47]
	v_mfma_f32_16x16x32_bf16 v[40:43], v[156:159], v[202:205], v[40:43]
	v_mfma_f32_16x16x32_bf16 v[28:31], v[148:151], v[210:213], v[28:31]
	v_mfma_f32_16x16x32_bf16 v[24:27], v[156:159], v[210:213], v[24:27]
	v_mfma_f32_16x16x32_bf16 v[12:15], v[148:151], v[234:237], v[12:15]
	v_mfma_f32_16x16x32_bf16 v[8:11], v[156:159], v[234:237], v[8:11]
	v_mfma_f32_16x16x32_bf16 v[60:63], v[152:155], v[198:201], v[60:63]
	v_mfma_f32_16x16x32_bf16 v[56:59], v[174:177], v[198:201], v[56:59]
	v_mfma_f32_16x16x32_bf16 v[44:47], v[152:155], v[206:209], v[44:47]
	v_mfma_f32_16x16x32_bf16 v[40:43], v[174:177], v[206:209], v[40:43]
	v_mfma_f32_16x16x32_bf16 v[28:31], v[152:155], v[222:225], v[28:31]
	v_mfma_f32_16x16x32_bf16 v[24:27], v[174:177], v[222:225], v[24:27]
	v_mfma_f32_16x16x32_bf16 v[12:15], v[152:155], v[238:241], v[12:15]
	v_mfma_f32_16x16x32_bf16 v[8:11], v[174:177], v[238:241], v[8:11]
	s_setprio 0
	s_setprio 1
	v_mfma_f32_16x16x32_bf16 v[52:55], v[178:181], v[194:197], v[52:55]
	v_mfma_f32_16x16x32_bf16 v[48:51], v[186:189], v[194:197], v[48:51]
	v_mfma_f32_16x16x32_bf16 v[36:39], v[178:181], v[202:205], v[36:39]
	v_mfma_f32_16x16x32_bf16 v[32:35], v[186:189], v[202:205], v[32:35]
	v_mfma_f32_16x16x32_bf16 v[20:23], v[178:181], v[210:213], v[20:23]
	v_mfma_f32_16x16x32_bf16 v[16:19], v[186:189], v[210:213], v[16:19]
	v_mfma_f32_16x16x32_bf16 v[4:7], v[178:181], v[234:237], v[4:7]
	v_mfma_f32_16x16x32_bf16 v[0:3], v[186:189], v[234:237], v[0:3]
	v_mfma_f32_16x16x32_bf16 v[52:55], v[182:185], v[198:201], v[52:55]
	v_mfma_f32_16x16x32_bf16 v[48:51], v[190:193], v[198:201], v[48:51]
	v_mfma_f32_16x16x32_bf16 v[36:39], v[182:185], v[206:209], v[36:39]
	v_mfma_f32_16x16x32_bf16 v[32:35], v[190:193], v[206:209], v[32:35]
	v_mfma_f32_16x16x32_bf16 v[20:23], v[182:185], v[222:225], v[20:23]
	v_mfma_f32_16x16x32_bf16 v[16:19], v[190:193], v[222:225], v[16:19]
	v_mfma_f32_16x16x32_bf16 v[4:7], v[182:185], v[238:241], v[4:7]
	v_mfma_f32_16x16x32_bf16 v[0:3], v[190:193], v[238:241], v[0:3]
	s_setprio 0
	s_barrier
	s_add_i32 s41, s41, 2
	s_add_u32 s42, s42, 0x100
	s_addc_u32 s43, s43, 0
	s_add_u32 s24, s24, 0x100
	s_addc_u32 s25, s25, 0
	s_cmp_gt_u32 s41, 13

.LBB0_377:
	s_add_u32 s40, s82, 0x80
	s_addc_u32 s41, s83, 0
	s_add_u32 s4, s84, 0x100
	s_addc_u32 s84, s85, 0
	s_mov_b32 s82, 0
	s_add_i32 s85, s82, 2
	s_add_u32 vcc_lo, s40, 0x80
	s_addc_u32 s83, s41, 0
	s_add_i32 s28, 0, 0x10000
	s_cmp_eq_u32 s95, s82
	s_cselect_b32 s83, s19, s83
	s_cselect_b32 s82, s18, vcc_lo
	s_cselect_b32 vcc_hi, s43, s84
	s_cselect_b32 vcc_lo, s42, s4
	s_add_i32 s22, 0, 0x14000
	v_add_u32_e32 v140, s28, v169
	v_add_u32_e32 v162, s22, v169
	ds_read_b128 v[128:131], v140
	ds_read_b128 v[132:135], v140 offset:1024
	ds_read_b128 v[136:139], v140 offset:2048
	ds_read_b128 v[140:143], v140 offset:3072
	ds_read_b128 v[144:147], v162
	ds_read_b128 v[148:151], v162 offset:1024
	ds_read_b128 v[152:155], v162 offset:2048
	ds_read_b128 v[180:183], v162 offset:3072
	v_lshl_add_u64 v[162:163], s[40:41], 0, v[176:177]
	s_add_i32 m0, s86, 0xc000
	ds_read_b128 v[184:187], v205
	ds_read_b128 v[188:191], v205 offset:1024
	ds_read_b128 v[192:195], v205 offset:2048
	ds_read_b128 v[196:199], v205 offset:3072
	ds_read_b128 v[206:209], v205 offset:4096
	ds_read_b128 v[210:213], v205 offset:5120
	ds_read_b128 v[222:225], v205 offset:6144
	ds_read_b128 v[234:237], v205 offset:7168
	global_load_lds_dwordx4 v[162:163], off
	v_lshl_add_u64 v[162:163], s[40:41], 0, v[178:179]
	s_add_i32 m0, s86, 0xe000
	s_nop 0
	global_load_lds_dwordx4 v[162:163], off
	s_waitcnt vmcnt(8)
	s_waitcnt lgkmcnt(0)
	s_barrier
	s_setprio 1
	s_waitcnt lgkmcnt(0)
	v_mfma_f32_16x16x32_bf16 v[124:127], v[128:131], v[184:187], 0
	v_mfma_f32_16x16x32_bf16 v[120:123], v[136:139], v[184:187], 0
	v_mfma_f32_16x16x32_bf16 v[108:111], v[128:131], v[192:195], 0
	v_mfma_f32_16x16x32_bf16 v[104:107], v[136:139], v[192:195], 0
	v_mfma_f32_16x16x32_bf16 v[92:95], v[128:131], v[206:209], 0
	v_mfma_f32_16x16x32_bf16 v[88:91], v[136:139], v[206:209], 0
	v_mfma_f32_16x16x32_bf16 v[76:79], v[128:131], v[222:225], 0
	v_mfma_f32_16x16x32_bf16 v[72:75], v[136:139], v[222:225], 0
	v_mfma_f32_16x16x32_bf16 v[124:127], v[132:135], v[188:191], v[124:127]
	v_mfma_f32_16x16x32_bf16 v[120:123], v[140:143], v[188:191], v[120:123]
	v_mfma_f32_16x16x32_bf16 v[108:111], v[132:135], v[196:199], v[108:111]
	v_mfma_f32_16x16x32_bf16 v[104:107], v[140:143], v[196:199], v[104:107]
	v_mfma_f32_16x16x32_bf16 v[92:95], v[132:135], v[210:213], v[92:95]
	v_mfma_f32_16x16x32_bf16 v[88:91], v[140:143], v[210:213], v[88:91]
	v_mfma_f32_16x16x32_bf16 v[76:79], v[132:135], v[234:237], v[76:79]
	v_mfma_f32_16x16x32_bf16 v[72:75], v[140:143], v[234:237], v[72:75]
	s_setprio 0
	s_setprio 1
	v_mfma_f32_16x16x32_bf16 v[116:119], v[144:147], v[184:187], 0
	v_mfma_f32_16x16x32_bf16 v[112:115], v[152:155], v[184:187], 0
	v_mfma_f32_16x16x32_bf16 v[100:103], v[144:147], v[192:195], 0
	v_mfma_f32_16x16x32_bf16 v[96:99], v[152:155], v[192:195], 0
	v_mfma_f32_16x16x32_bf16 v[84:87], v[144:147], v[206:209], 0
	v_mfma_f32_16x16x32_bf16 v[80:83], v[152:155], v[206:209], 0
	v_mfma_f32_16x16x32_bf16 v[68:71], v[144:147], v[222:225], 0
	v_mfma_f32_16x16x32_bf16 v[64:67], v[152:155], v[222:225], 0
	v_mfma_f32_16x16x32_bf16 v[116:119], v[148:151], v[188:191], v[116:119]
	v_mfma_f32_16x16x32_bf16 v[112:115], v[180:183], v[188:191], v[112:115]
	v_mfma_f32_16x16x32_bf16 v[100:103], v[148:151], v[196:199], v[100:103]
	v_mfma_f32_16x16x32_bf16 v[96:99], v[180:183], v[196:199], v[96:99]
	v_mfma_f32_16x16x32_bf16 v[84:87], v[148:151], v[210:213], v[84:87]
	v_mfma_f32_16x16x32_bf16 v[80:83], v[180:183], v[210:213], v[80:83]
	v_mfma_f32_16x16x32_bf16 v[68:71], v[148:151], v[234:237], v[68:71]
	v_mfma_f32_16x16x32_bf16 v[64:67], v[180:183], v[234:237], v[64:67]
	s_setprio 0
	s_barrier
	s_add_i32 s23, s28, s81
	v_lshl_add_u64 v[162:163], vcc, 0, v[160:161]
	s_mov_b32 m0, s23
	ds_read_b128 v[184:187], v205 offset:16384
	ds_read_b128 v[188:191], v205 offset:17408
	ds_read_b128 v[192:195], v205 offset:18432
	ds_read_b128 v[196:199], v205 offset:19456
	ds_read_b128 v[206:209], v205 offset:20480
	ds_read_b128 v[210:213], v205 offset:21504
	ds_read_b128 v[222:225], v205 offset:22528
	ds_read_b128 v[234:237], v205 offset:23552
	global_load_lds_dwordx4 v[162:163], off
	s_add_i32 m0, s23, 0x2000
	v_lshl_add_u64 v[164:165], vcc, 0, v[170:171]
	s_add_u32 vcc_lo, vcc_lo, s8
	s_addc_u32 vcc_hi, vcc_hi, 0
	s_add_i32 s22, s22, s81
	global_load_lds_dwordx4 v[164:165], off
	v_lshl_add_u64 v[200:201], vcc, 0, v[160:161]
	s_mov_b32 m0, s22
	v_lshl_add_u64 v[214:215], vcc, 0, v[170:171]
	global_load_lds_dwordx4 v[200:201], off
	s_add_i32 m0, s22, 0x2000
	v_lshl_add_u64 v[226:227], s[82:83], 0, v[156:157]
	global_load_lds_dwordx4 v[214:215], off
	s_mov_b32 m0, s86
	v_lshl_add_u64 v[238:239], s[82:83], 0, v[158:159]
	global_load_lds_dwordx4 v[226:227], off
	s_mov_b32 m0, s87
	s_nop 0
	global_load_lds_dwordx4 v[238:239], off
	s_waitcnt vmcnt(8)
	s_waitcnt lgkmcnt(0)
	s_barrier
	s_setprio 1
	s_waitcnt lgkmcnt(0)
	v_mfma_f32_16x16x32_bf16 v[60:63], v[128:131], v[184:187], 0
	v_mfma_f32_16x16x32_bf16 v[56:59], v[136:139], v[184:187], 0
	v_mfma_f32_16x16x32_bf16 v[44:47], v[128:131], v[192:195], 0
	v_mfma_f32_16x16x32_bf16 v[40:43], v[136:139], v[192:195], 0
	v_mfma_f32_16x16x32_bf16 v[28:31], v[128:131], v[206:209], 0
	v_mfma_f32_16x16x32_bf16 v[24:27], v[136:139], v[206:209], 0
	v_mfma_f32_16x16x32_bf16 v[12:15], v[128:131], v[222:225], 0
	v_mfma_f32_16x16x32_bf16 v[8:11], v[136:139], v[222:225], 0
	v_mfma_f32_16x16x32_bf16 v[60:63], v[132:135], v[188:191], v[60:63]
	v_mfma_f32_16x16x32_bf16 v[56:59], v[140:143], v[188:191], v[56:59]
	v_mfma_f32_16x16x32_bf16 v[44:47], v[132:135], v[196:199], v[44:47]
	v_mfma_f32_16x16x32_bf16 v[40:43], v[140:143], v[196:199], v[40:43]
	v_mfma_f32_16x16x32_bf16 v[28:31], v[132:135], v[210:213], v[28:31]
	v_mfma_f32_16x16x32_bf16 v[24:27], v[140:143], v[210:213], v[24:27]
	v_mfma_f32_16x16x32_bf16 v[12:15], v[132:135], v[234:237], v[12:15]
	v_mfma_f32_16x16x32_bf16 v[8:11], v[140:143], v[234:237], v[8:11]
	s_setprio 0
	s_setprio 1
	v_mfma_f32_16x16x32_bf16 v[52:55], v[144:147], v[184:187], 0
	v_mfma_f32_16x16x32_bf16 v[48:51], v[152:155], v[184:187], 0
	v_mfma_f32_16x16x32_bf16 v[36:39], v[144:147], v[192:195], 0
	v_mfma_f32_16x16x32_bf16 v[32:35], v[152:155], v[192:195], 0
	v_mfma_f32_16x16x32_bf16 v[20:23], v[144:147], v[206:209], 0
	v_mfma_f32_16x16x32_bf16 v[16:19], v[152:155], v[206:209], 0
	v_mfma_f32_16x16x32_bf16 v[4:7], v[144:147], v[222:225], 0
	v_mfma_f32_16x16x32_bf16 v[0:3], v[152:155], v[222:225], 0
	v_mfma_f32_16x16x32_bf16 v[52:55], v[148:151], v[188:191], v[52:55]
	v_mfma_f32_16x16x32_bf16 v[48:51], v[180:183], v[188:191], v[48:51]
	v_mfma_f32_16x16x32_bf16 v[36:39], v[148:151], v[196:199], v[36:39]
	v_mfma_f32_16x16x32_bf16 v[32:35], v[180:183], v[196:199], v[32:35]
	v_mfma_f32_16x16x32_bf16 v[20:23], v[148:151], v[210:213], v[20:23]
	v_mfma_f32_16x16x32_bf16 v[16:19], v[180:183], v[210:213], v[16:19]
	v_mfma_f32_16x16x32_bf16 v[4:7], v[148:151], v[234:237], v[4:7]
	v_mfma_f32_16x16x32_bf16 v[0:3], v[180:183], v[234:237], v[0:3]
	s_setprio 0
	s_barrier
	s_add_i32 s22, 0, 0x18000
	s_add_i32 s23, 0, 0x1c000
	v_add_u32_e32 v140, s22, v169
	v_add_u32_e32 v173, s23, v169
	ds_read_b128 v[128:131], v140
	ds_read_b128 v[132:135], v140 offset:1024
	ds_read_b128 v[136:139], v140 offset:2048
	ds_read_b128 v[140:143], v140 offset:3072
	ds_read_b128 v[144:147], v173
	ds_read_b128 v[148:151], v173 offset:1024
	ds_read_b128 v[152:155], v173 offset:2048
	ds_read_b128 v[180:183], v173 offset:3072
	s_add_u32 s82, s82, s8
	s_addc_u32 s83, s83, 0
	s_mov_b32 m0, s88
	v_lshl_add_u64 v[240:241], s[82:83], 0, v[156:157]
	ds_read_b128 v[184:187], v205 offset:32768
	ds_read_b128 v[188:191], v205 offset:33792
	ds_read_b128 v[192:195], v205 offset:34816
	ds_read_b128 v[196:199], v205 offset:35840
	ds_read_b128 v[206:209], v205 offset:36864
	ds_read_b128 v[210:213], v205 offset:37888
	ds_read_b128 v[222:225], v205 offset:38912
	ds_read_b128 v[234:237], v205 offset:39936
	global_load_lds_dwordx4 v[240:241], off
	v_lshl_add_u64 v[240:241], s[82:83], 0, v[158:159]
	s_mov_b32 m0, s89
	s_nop 0
	global_load_lds_dwordx4 v[240:241], off
	s_waitcnt vmcnt(8)
	s_waitcnt lgkmcnt(0)
	s_barrier
	s_setprio 1
	s_waitcnt lgkmcnt(0)
	v_mfma_f32_16x16x32_bf16 v[124:127], v[128:131], v[184:187], v[124:127]
	v_mfma_f32_16x16x32_bf16 v[120:123], v[136:139], v[184:187], v[120:123]
	v_mfma_f32_16x16x32_bf16 v[108:111], v[128:131], v[192:195], v[108:111]
	v_mfma_f32_16x16x32_bf16 v[104:107], v[136:139], v[192:195], v[104:107]
	v_mfma_f32_16x16x32_bf16 v[92:95], v[128:131], v[206:209], v[92:95]
	v_mfma_f32_16x16x32_bf16 v[88:91], v[136:139], v[206:209], v[88:91]
	v_mfma_f32_16x16x32_bf16 v[76:79], v[128:131], v[222:225], v[76:79]
	v_mfma_f32_16x16x32_bf16 v[72:75], v[136:139], v[222:225], v[72:75]
	v_mfma_f32_16x16x32_bf16 v[124:127], v[132:135], v[188:191], v[124:127]
	v_mfma_f32_16x16x32_bf16 v[120:123], v[140:143], v[188:191], v[120:123]
	v_mfma_f32_16x16x32_bf16 v[108:111], v[132:135], v[196:199], v[108:111]
	v_mfma_f32_16x16x32_bf16 v[104:107], v[140:143], v[196:199], v[104:107]
	v_mfma_f32_16x16x32_bf16 v[92:95], v[132:135], v[210:213], v[92:95]
	v_mfma_f32_16x16x32_bf16 v[88:91], v[140:143], v[210:213], v[88:91]
	v_mfma_f32_16x16x32_bf16 v[76:79], v[132:135], v[234:237], v[76:79]
	v_mfma_f32_16x16x32_bf16 v[72:75], v[140:143], v[234:237], v[72:75]
	s_setprio 0
	s_setprio 1
	v_mfma_f32_16x16x32_bf16 v[116:119], v[144:147], v[184:187], v[116:119]
	v_mfma_f32_16x16x32_bf16 v[112:115], v[152:155], v[184:187], v[112:115]
	v_mfma_f32_16x16x32_bf16 v[100:103], v[144:147], v[192:195], v[100:103]
	v_mfma_f32_16x16x32_bf16 v[96:99], v[152:155], v[192:195], v[96:99]
	v_mfma_f32_16x16x32_bf16 v[84:87], v[144:147], v[206:209], v[84:87]
	v_mfma_f32_16x16x32_bf16 v[80:83], v[152:155], v[206:209], v[80:83]
	v_mfma_f32_16x16x32_bf16 v[68:71], v[144:147], v[222:225], v[68:71]
	v_mfma_f32_16x16x32_bf16 v[64:67], v[152:155], v[222:225], v[64:67]
	v_mfma_f32_16x16x32_bf16 v[116:119], v[148:151], v[188:191], v[116:119]
	v_mfma_f32_16x16x32_bf16 v[112:115], v[180:183], v[188:191], v[112:115]
	v_mfma_f32_16x16x32_bf16 v[100:103], v[148:151], v[196:199], v[100:103]
	v_mfma_f32_16x16x32_bf16 v[96:99], v[180:183], v[196:199], v[96:99]
	v_mfma_f32_16x16x32_bf16 v[84:87], v[148:151], v[210:213], v[84:87]
	v_mfma_f32_16x16x32_bf16 v[80:83], v[180:183], v[210:213], v[80:83]
	v_mfma_f32_16x16x32_bf16 v[68:71], v[148:151], v[234:237], v[68:71]
	v_mfma_f32_16x16x32_bf16 v[64:67], v[180:183], v[234:237], v[64:67]
	s_setprio 0
	s_barrier
	s_add_i32 s22, s22, s81
	v_lshl_add_u64 v[162:163], v[162:163], 0, s[48:49]
	s_mov_b32 m0, s22
	ds_read_b128 v[184:187], v205 offset:49152
	ds_read_b128 v[188:191], v205 offset:50176
	ds_read_b128 v[192:195], v205 offset:51200
	ds_read_b128 v[196:199], v205 offset:52224
	ds_read_b128 v[206:209], v205 offset:53248
	ds_read_b128 v[210:213], v205 offset:54272
	ds_read_b128 v[222:225], v205 offset:55296
	ds_read_b128 v[234:237], v205 offset:56320
	global_load_lds_dwordx4 v[162:163], off
	v_lshl_add_u64 v[162:163], v[164:165], 0, s[48:49]
	s_add_i32 m0, s22, 0x2000
	s_add_i32 s22, s23, s81
	global_load_lds_dwordx4 v[162:163], off
	v_lshl_add_u64 v[162:163], v[200:201], 0, s[48:49]
	s_mov_b32 m0, s22
	s_nop 0
	global_load_lds_dwordx4 v[162:163], off
	v_lshl_add_u64 v[162:163], v[214:215], 0, s[48:49]
	s_add_i32 m0, s22, 0x2000
	s_nop 0
	global_load_lds_dwordx4 v[162:163], off
	v_lshl_add_u64 v[162:163], v[226:227], 0, s[48:49]
	s_mov_b32 m0, s90
	s_nop 0
	global_load_lds_dwordx4 v[162:163], off
	v_lshl_add_u64 v[162:163], v[238:239], 0, s[48:49]
	s_mov_b32 m0, s91
	s_nop 0
	global_load_lds_dwordx4 v[162:163], off
	s_waitcnt vmcnt(8)
	s_waitcnt lgkmcnt(0)
	s_barrier
	s_setprio 1
	s_waitcnt lgkmcnt(0)
	v_mfma_f32_16x16x32_bf16 v[60:63], v[128:131], v[184:187], v[60:63]
	v_mfma_f32_16x16x32_bf16 v[56:59], v[136:139], v[184:187], v[56:59]
	v_mfma_f32_16x16x32_bf16 v[44:47], v[128:131], v[192:195], v[44:47]
	v_mfma_f32_16x16x32_bf16 v[40:43], v[136:139], v[192:195], v[40:43]
	v_mfma_f32_16x16x32_bf16 v[28:31], v[128:131], v[206:209], v[28:31]
	v_mfma_f32_16x16x32_bf16 v[24:27], v[136:139], v[206:209], v[24:27]
	v_mfma_f32_16x16x32_bf16 v[12:15], v[128:131], v[222:225], v[12:15]
	v_mfma_f32_16x16x32_bf16 v[8:11], v[136:139], v[222:225], v[8:11]
	v_mfma_f32_16x16x32_bf16 v[60:63], v[132:135], v[188:191], v[60:63]
	v_mfma_f32_16x16x32_bf16 v[56:59], v[140:143], v[188:191], v[56:59]
	v_mfma_f32_16x16x32_bf16 v[44:47], v[132:135], v[196:199], v[44:47]
	v_mfma_f32_16x16x32_bf16 v[40:43], v[140:143], v[196:199], v[40:43]
	v_mfma_f32_16x16x32_bf16 v[28:31], v[132:135], v[210:213], v[28:31]
	v_mfma_f32_16x16x32_bf16 v[24:27], v[140:143], v[210:213], v[24:27]
	v_mfma_f32_16x16x32_bf16 v[12:15], v[132:135], v[234:237], v[12:15]
	v_mfma_f32_16x16x32_bf16 v[8:11], v[140:143], v[234:237], v[8:11]
	s_setprio 0
	s_setprio 1
	v_mfma_f32_16x16x32_bf16 v[52:55], v[144:147], v[184:187], v[52:55]
	v_mfma_f32_16x16x32_bf16 v[48:51], v[152:155], v[184:187], v[48:51]
	v_mfma_f32_16x16x32_bf16 v[36:39], v[144:147], v[192:195], v[36:39]
	v_mfma_f32_16x16x32_bf16 v[32:35], v[152:155], v[192:195], v[32:35]
	v_mfma_f32_16x16x32_bf16 v[20:23], v[144:147], v[206:209], v[20:23]
	v_mfma_f32_16x16x32_bf16 v[16:19], v[152:155], v[206:209], v[16:19]
	v_mfma_f32_16x16x32_bf16 v[4:7], v[144:147], v[222:225], v[4:7]
	v_mfma_f32_16x16x32_bf16 v[0:3], v[152:155], v[222:225], v[0:3]
	v_mfma_f32_16x16x32_bf16 v[52:55], v[148:151], v[188:191], v[52:55]
	v_mfma_f32_16x16x32_bf16 v[48:51], v[180:183], v[188:191], v[48:51]
	v_mfma_f32_16x16x32_bf16 v[36:39], v[148:151], v[196:199], v[36:39]
	v_mfma_f32_16x16x32_bf16 v[32:35], v[180:183], v[196:199], v[32:35]
	v_mfma_f32_16x16x32_bf16 v[20:23], v[148:151], v[210:213], v[20:23]
	v_mfma_f32_16x16x32_bf16 v[16:19], v[180:183], v[210:213], v[16:19]
	v_mfma_f32_16x16x32_bf16 v[4:7], v[148:151], v[234:237], v[4:7]
	v_mfma_f32_16x16x32_bf16 v[0:3], v[180:183], v[234:237], v[0:3]
	s_setprio 0
	s_barrier
	s_add_u32 s40, s40, 0x100
	s_addc_u32 s41, s41, 0
	s_add_u32 s4, s4, 0x100
	s_addc_u32 s84, s84, 0
	s_cmp_ge_u32 s85, s94
	s_mov_b32 s82, s85

.LBB0_654:
	s_ashr_i32 s17, s16, 31
	s_lshl_b64 s[18:19], s[16:17], 19
	s_add_u32 s18, s68, s18
	s_addc_u32 s19, s69, s19
	s_and_b64 s[36:37], s[12:13], exec
	s_cselect_b32 s17, s19, s39
	s_cselect_b32 s84, s18, s38
	s_ashr_i32 s15, s14, 31
	s_lshl_b64 s[36:37], s[14:15], 19
	s_add_u32 s36, s28, s36
	s_addc_u32 s37, s66, s37
	s_and_b64 s[42:43], s[12:13], exec
	s_cselect_b32 s15, s37, s41
	s_cselect_b32 s85, s36, s40
	s_add_u32 s38, s38, 0x40080
	s_addc_u32 s39, s39, 0
	s_add_u32 s86, s40, 0x100
	s_addc_u32 s87, s41, 0
	s_mov_b32 s88, -2
	s_add_u32 s40, s38, 0xfffc0080
	s_addc_u32 s41, s39, -1
	s_add_i32 s89, 0, 0x10000
	s_cmp_eq_u32 s88, 12
	s_cselect_b32 s43, s17, s41
	s_cselect_b32 s42, s84, s40
	v_add_u32_e32 v143, s89, v141
	s_cselect_b32 s41, s15, s87
	s_cselect_b32 s40, s85, s86
	s_add_i32 s92, 0, 0x14000
	ds_read_b128 v[144:147], v143
	ds_read_b128 v[148:151], v143 offset:1024
	ds_read_b128 v[152:155], v143 offset:2048
	ds_read_b128 v[156:159], v143 offset:3072
	v_add_u32_e32 v143, s92, v141
	ds_read_b128 v[170:173], v143
	ds_read_b128 v[174:177], v143 offset:1024
	ds_read_b128 v[178:181], v143 offset:2048
	ds_read_b128 v[182:185], v143 offset:3072
	v_lshl_add_u64 v[162:163], s[38:39], 0, v[136:137]
	s_add_i32 m0, s27, 0xc000
	ds_read_b128 v[186:189], v142
	ds_read_b128 v[190:193], v142 offset:1024
	ds_read_b128 v[194:197], v142 offset:2048
	ds_read_b128 v[198:201], v142 offset:3072
	ds_read_b128 v[202:205], v142 offset:4096
	ds_read_b128 v[206:209], v142 offset:5120
	ds_read_b128 v[210:213], v142 offset:6144
	ds_read_b128 v[222:225], v142 offset:7168
	global_load_lds_dwordx4 v[162:163], off
	v_lshl_add_u64 v[162:163], s[38:39], 0, v[138:139]
	s_add_i32 m0, s27, 0xe000
	s_nop 0
	global_load_lds_dwordx4 v[162:163], off
	s_waitcnt vmcnt(8)
	s_waitcnt lgkmcnt(0)
	s_barrier
	s_setprio 1
	s_waitcnt lgkmcnt(0)
	v_mfma_f32_16x16x32_bf16 v[124:127], v[144:147], v[186:189], 0
	v_mfma_f32_16x16x32_bf16 v[120:123], v[152:155], v[186:189], 0
	v_mfma_f32_16x16x32_bf16 v[116:119], v[144:147], v[194:197], 0
	v_mfma_f32_16x16x32_bf16 v[112:115], v[152:155], v[194:197], 0
	v_mfma_f32_16x16x32_bf16 v[100:103], v[144:147], v[202:205], 0
	v_mfma_f32_16x16x32_bf16 v[96:99], v[152:155], v[202:205], 0
	v_mfma_f32_16x16x32_bf16 v[84:87], v[144:147], v[210:213], 0
	v_mfma_f32_16x16x32_bf16 v[80:83], v[152:155], v[210:213], 0
	v_mfma_f32_16x16x32_bf16 v[124:127], v[148:151], v[190:193], v[124:127]
	v_mfma_f32_16x16x32_bf16 v[120:123], v[156:159], v[190:193], v[120:123]
	v_mfma_f32_16x16x32_bf16 v[116:119], v[148:151], v[198:201], v[116:119]
	v_mfma_f32_16x16x32_bf16 v[112:115], v[156:159], v[198:201], v[112:115]
	v_mfma_f32_16x16x32_bf16 v[100:103], v[148:151], v[206:209], v[100:103]
	v_mfma_f32_16x16x32_bf16 v[96:99], v[156:159], v[206:209], v[96:99]
	v_mfma_f32_16x16x32_bf16 v[84:87], v[148:151], v[222:225], v[84:87]
	v_mfma_f32_16x16x32_bf16 v[80:83], v[156:159], v[222:225], v[80:83]
	s_setprio 0
	s_setprio 1
	v_mfma_f32_16x16x32_bf16 v[108:111], v[170:173], v[186:189], 0
	v_mfma_f32_16x16x32_bf16 v[104:107], v[178:181], v[186:189], 0
	v_mfma_f32_16x16x32_bf16 v[92:95], v[170:173], v[194:197], 0
	v_mfma_f32_16x16x32_bf16 v[88:91], v[178:181], v[194:197], 0
	v_mfma_f32_16x16x32_bf16 v[76:79], v[170:173], v[202:205], 0
	v_mfma_f32_16x16x32_bf16 v[72:75], v[178:181], v[202:205], 0
	v_mfma_f32_16x16x32_bf16 v[68:71], v[170:173], v[210:213], 0
	v_mfma_f32_16x16x32_bf16 v[64:67], v[178:181], v[210:213], 0
	v_mfma_f32_16x16x32_bf16 v[108:111], v[174:177], v[190:193], v[108:111]
	v_mfma_f32_16x16x32_bf16 v[104:107], v[182:185], v[190:193], v[104:107]
	v_mfma_f32_16x16x32_bf16 v[92:95], v[174:177], v[198:201], v[92:95]
	v_mfma_f32_16x16x32_bf16 v[88:91], v[182:185], v[198:201], v[88:91]
	v_mfma_f32_16x16x32_bf16 v[76:79], v[174:177], v[206:209], v[76:79]
	v_mfma_f32_16x16x32_bf16 v[72:75], v[182:185], v[206:209], v[72:75]
	v_mfma_f32_16x16x32_bf16 v[68:71], v[174:177], v[222:225], v[68:71]
	v_mfma_f32_16x16x32_bf16 v[64:67], v[182:185], v[222:225], v[64:67]
	s_setprio 0
	s_barrier
	s_add_i32 s89, s89, s26
	v_lshl_add_u64 v[162:163], s[40:41], 0, v[130:131]
	s_mov_b32 m0, s89
	ds_read_b128 v[186:189], v142 offset:16384
	ds_read_b128 v[190:193], v142 offset:17408
	ds_read_b128 v[194:197], v142 offset:18432
	ds_read_b128 v[198:201], v142 offset:19456
	ds_read_b128 v[202:205], v142 offset:20480
	ds_read_b128 v[206:209], v142 offset:21504
	ds_read_b128 v[210:213], v142 offset:22528
	ds_read_b128 v[222:225], v142 offset:23552
	global_load_lds_dwordx4 v[162:163], off
	s_add_i32 m0, s89, 0x2000
	s_add_u32 s90, s40, 0x40000
	v_lshl_add_u64 v[164:165], s[40:41], 0, v[134:135]
	s_addc_u32 s91, s41, 0
	s_add_i32 s89, s92, s26
	global_load_lds_dwordx4 v[164:165], off
	v_lshl_add_u64 v[214:215], s[90:91], 0, v[130:131]
	s_mov_b32 m0, s89
	v_lshl_add_u64 v[226:227], s[42:43], 0, v[132:133]
	global_load_lds_dwordx4 v[214:215], off
	v_lshl_add_u64 v[214:215], s[90:91], 0, v[134:135]
	s_add_i32 m0, s89, 0x2000
	s_nop 0
	global_load_lds_dwordx4 v[214:215], off
	v_lshl_add_u64 v[214:215], s[42:43], 0, v[128:129]
	s_mov_b32 m0, s27
	s_nop 0
	global_load_lds_dwordx4 v[214:215], off
	s_mov_b32 m0, s50
	s_nop 0
	global_load_lds_dwordx4 v[226:227], off
	s_waitcnt vmcnt(8)
	s_waitcnt lgkmcnt(0)
	s_barrier
	s_setprio 1
	s_waitcnt lgkmcnt(0)
	v_mfma_f32_16x16x32_bf16 v[60:63], v[144:147], v[186:189], 0
	v_mfma_f32_16x16x32_bf16 v[56:59], v[152:155], v[186:189], 0
	v_mfma_f32_16x16x32_bf16 v[52:55], v[144:147], v[194:197], 0
	v_mfma_f32_16x16x32_bf16 v[48:51], v[152:155], v[194:197], 0
	v_mfma_f32_16x16x32_bf16 v[36:39], v[144:147], v[202:205], 0
	v_mfma_f32_16x16x32_bf16 v[32:35], v[152:155], v[202:205], 0
	v_mfma_f32_16x16x32_bf16 v[20:23], v[144:147], v[210:213], 0
	v_mfma_f32_16x16x32_bf16 v[16:19], v[152:155], v[210:213], 0
	v_mfma_f32_16x16x32_bf16 v[60:63], v[148:151], v[190:193], v[60:63]
	v_mfma_f32_16x16x32_bf16 v[56:59], v[156:159], v[190:193], v[56:59]
	v_mfma_f32_16x16x32_bf16 v[52:55], v[148:151], v[198:201], v[52:55]
	v_mfma_f32_16x16x32_bf16 v[48:51], v[156:159], v[198:201], v[48:51]
	v_mfma_f32_16x16x32_bf16 v[36:39], v[148:151], v[206:209], v[36:39]
	v_mfma_f32_16x16x32_bf16 v[32:35], v[156:159], v[206:209], v[32:35]
	v_mfma_f32_16x16x32_bf16 v[20:23], v[148:151], v[222:225], v[20:23]
	v_mfma_f32_16x16x32_bf16 v[16:19], v[156:159], v[222:225], v[16:19]
	s_setprio 0
	s_setprio 1
	v_mfma_f32_16x16x32_bf16 v[44:47], v[170:173], v[186:189], 0
	v_mfma_f32_16x16x32_bf16 v[40:43], v[178:181], v[186:189], 0
	v_mfma_f32_16x16x32_bf16 v[28:31], v[170:173], v[194:197], 0
	v_mfma_f32_16x16x32_bf16 v[24:27], v[178:181], v[194:197], 0
	v_mfma_f32_16x16x32_bf16 v[12:15], v[170:173], v[202:205], 0
	v_mfma_f32_16x16x32_bf16 v[8:11], v[178:181], v[202:205], 0
	v_mfma_f32_16x16x32_bf16 v[4:7], v[170:173], v[210:213], 0
	v_mfma_f32_16x16x32_bf16 v[0:3], v[178:181], v[210:213], 0
	v_mfma_f32_16x16x32_bf16 v[44:47], v[174:177], v[190:193], v[44:47]
	v_mfma_f32_16x16x32_bf16 v[40:43], v[182:185], v[190:193], v[40:43]
	v_mfma_f32_16x16x32_bf16 v[28:31], v[174:177], v[198:201], v[28:31]
	v_mfma_f32_16x16x32_bf16 v[24:27], v[182:185], v[198:201], v[24:27]
	v_mfma_f32_16x16x32_bf16 v[12:15], v[174:177], v[206:209], v[12:15]
	v_mfma_f32_16x16x32_bf16 v[8:11], v[182:185], v[206:209], v[8:11]
	v_mfma_f32_16x16x32_bf16 v[4:7], v[174:177], v[222:225], v[4:7]
	v_mfma_f32_16x16x32_bf16 v[0:3], v[182:185], v[222:225], v[0:3]
	s_setprio 0
	s_barrier
	s_add_i32 s89, 0, 0x18000
	v_add_u32_e32 v143, s89, v141
	s_add_i32 s90, 0, 0x1c000
	ds_read_b128 v[144:147], v143
	ds_read_b128 v[148:151], v143 offset:1024
	ds_read_b128 v[152:155], v143 offset:2048
	ds_read_b128 v[156:159], v143 offset:3072
	v_add_u32_e32 v143, s90, v141
	ds_read_b128 v[170:173], v143
	ds_read_b128 v[174:177], v143 offset:1024
	ds_read_b128 v[178:181], v143 offset:2048
	ds_read_b128 v[182:185], v143 offset:3072
	s_add_u32 s42, s42, 0x40000
	s_addc_u32 s43, s43, 0
	s_mov_b32 m0, s51
	v_lshl_add_u64 v[234:235], s[42:43], 0, v[128:129]
	ds_read_b128 v[186:189], v142 offset:32768
	ds_read_b128 v[190:193], v142 offset:33792
	ds_read_b128 v[194:197], v142 offset:34816
	ds_read_b128 v[198:201], v142 offset:35840
	ds_read_b128 v[202:205], v142 offset:36864
	ds_read_b128 v[206:209], v142 offset:37888
	ds_read_b128 v[210:213], v142 offset:38912
	ds_read_b128 v[222:225], v142 offset:39936
	global_load_lds_dwordx4 v[234:235], off
	v_lshl_add_u64 v[234:235], s[42:43], 0, v[132:133]
	s_mov_b32 m0, s80
	s_nop 0
	global_load_lds_dwordx4 v[234:235], off
	s_waitcnt vmcnt(8)
	s_waitcnt lgkmcnt(0)
	s_barrier
	s_setprio 1
	s_waitcnt lgkmcnt(0)
	v_mfma_f32_16x16x32_bf16 v[124:127], v[144:147], v[186:189], v[124:127]
	v_mfma_f32_16x16x32_bf16 v[120:123], v[152:155], v[186:189], v[120:123]
	v_mfma_f32_16x16x32_bf16 v[116:119], v[144:147], v[194:197], v[116:119]
	v_mfma_f32_16x16x32_bf16 v[112:115], v[152:155], v[194:197], v[112:115]
	v_mfma_f32_16x16x32_bf16 v[100:103], v[144:147], v[202:205], v[100:103]
	v_mfma_f32_16x16x32_bf16 v[96:99], v[152:155], v[202:205], v[96:99]
	v_mfma_f32_16x16x32_bf16 v[84:87], v[144:147], v[210:213], v[84:87]
	v_mfma_f32_16x16x32_bf16 v[80:83], v[152:155], v[210:213], v[80:83]
	v_mfma_f32_16x16x32_bf16 v[124:127], v[148:151], v[190:193], v[124:127]
	v_mfma_f32_16x16x32_bf16 v[120:123], v[156:159], v[190:193], v[120:123]
	v_mfma_f32_16x16x32_bf16 v[116:119], v[148:151], v[198:201], v[116:119]
	v_mfma_f32_16x16x32_bf16 v[112:115], v[156:159], v[198:201], v[112:115]
	v_mfma_f32_16x16x32_bf16 v[100:103], v[148:151], v[206:209], v[100:103]
	v_mfma_f32_16x16x32_bf16 v[96:99], v[156:159], v[206:209], v[96:99]
	v_mfma_f32_16x16x32_bf16 v[84:87], v[148:151], v[222:225], v[84:87]
	v_mfma_f32_16x16x32_bf16 v[80:83], v[156:159], v[222:225], v[80:83]
	s_setprio 0
	s_setprio 1
	v_mfma_f32_16x16x32_bf16 v[108:111], v[170:173], v[186:189], v[108:111]
	v_mfma_f32_16x16x32_bf16 v[104:107], v[178:181], v[186:189], v[104:107]
	v_mfma_f32_16x16x32_bf16 v[92:95], v[170:173], v[194:197], v[92:95]
	v_mfma_f32_16x16x32_bf16 v[88:91], v[178:181], v[194:197], v[88:91]
	v_mfma_f32_16x16x32_bf16 v[76:79], v[170:173], v[202:205], v[76:79]
	v_mfma_f32_16x16x32_bf16 v[72:75], v[178:181], v[202:205], v[72:75]
	v_mfma_f32_16x16x32_bf16 v[68:71], v[170:173], v[210:213], v[68:71]
	v_mfma_f32_16x16x32_bf16 v[64:67], v[178:181], v[210:213], v[64:67]
	v_mfma_f32_16x16x32_bf16 v[108:111], v[174:177], v[190:193], v[108:111]
	v_mfma_f32_16x16x32_bf16 v[104:107], v[182:185], v[190:193], v[104:107]
	v_mfma_f32_16x16x32_bf16 v[92:95], v[174:177], v[198:201], v[92:95]
	v_mfma_f32_16x16x32_bf16 v[88:91], v[182:185], v[198:201], v[88:91]
	v_mfma_f32_16x16x32_bf16 v[76:79], v[174:177], v[206:209], v[76:79]
	v_mfma_f32_16x16x32_bf16 v[72:75], v[182:185], v[206:209], v[72:75]
	v_mfma_f32_16x16x32_bf16 v[68:71], v[174:177], v[222:225], v[68:71]
	v_mfma_f32_16x16x32_bf16 v[64:67], v[182:185], v[222:225], v[64:67]
	s_setprio 0
	s_barrier
	s_add_i32 s42, s89, s26
	v_lshl_add_u64 v[162:163], v[162:163], 0, s[48:49]
	s_mov_b32 m0, s42
	ds_read_b128 v[186:189], v142 offset:49152
	ds_read_b128 v[190:193], v142 offset:50176
	ds_read_b128 v[194:197], v142 offset:51200
	ds_read_b128 v[198:201], v142 offset:52224
	ds_read_b128 v[202:205], v142 offset:53248
	ds_read_b128 v[206:209], v142 offset:54272
	ds_read_b128 v[210:213], v142 offset:55296
	ds_read_b128 v[222:225], v142 offset:56320
	global_load_lds_dwordx4 v[162:163], off
	s_add_i32 m0, s42, 0x2000
	s_add_u32 s40, s40, 0x40080
	v_lshl_add_u64 v[162:163], v[164:165], 0, s[48:49]
	s_addc_u32 s41, s41, 0
	s_add_i32 s42, s90, s26
	global_load_lds_dwordx4 v[162:163], off
	v_lshl_add_u64 v[162:163], s[40:41], 0, v[130:131]
	s_mov_b32 m0, s42
	s_nop 0
	global_load_lds_dwordx4 v[162:163], off
	v_lshl_add_u64 v[162:163], s[40:41], 0, v[134:135]
	s_add_i32 m0, s42, 0x2000
	s_nop 0
	global_load_lds_dwordx4 v[162:163], off
	v_lshl_add_u64 v[162:163], v[214:215], 0, s[48:49]
	s_mov_b32 m0, s81
	s_nop 0
	global_load_lds_dwordx4 v[162:163], off
	v_lshl_add_u64 v[162:163], v[226:227], 0, s[48:49]
	s_mov_b32 m0, s82
	s_nop 0
	global_load_lds_dwordx4 v[162:163], off
	s_waitcnt vmcnt(8)
	s_waitcnt lgkmcnt(0)
	s_barrier
	s_setprio 1
	s_waitcnt lgkmcnt(0)
	v_mfma_f32_16x16x32_bf16 v[60:63], v[144:147], v[186:189], v[60:63]
	v_mfma_f32_16x16x32_bf16 v[56:59], v[152:155], v[186:189], v[56:59]
	v_mfma_f32_16x16x32_bf16 v[52:55], v[144:147], v[194:197], v[52:55]
	v_mfma_f32_16x16x32_bf16 v[48:51], v[152:155], v[194:197], v[48:51]
	v_mfma_f32_16x16x32_bf16 v[36:39], v[144:147], v[202:205], v[36:39]
	v_mfma_f32_16x16x32_bf16 v[32:35], v[152:155], v[202:205], v[32:35]
	v_mfma_f32_16x16x32_bf16 v[20:23], v[144:147], v[210:213], v[20:23]
	v_mfma_f32_16x16x32_bf16 v[16:19], v[152:155], v[210:213], v[16:19]
	v_mfma_f32_16x16x32_bf16 v[60:63], v[148:151], v[190:193], v[60:63]
	v_mfma_f32_16x16x32_bf16 v[56:59], v[156:159], v[190:193], v[56:59]
	v_mfma_f32_16x16x32_bf16 v[52:55], v[148:151], v[198:201], v[52:55]
	v_mfma_f32_16x16x32_bf16 v[48:51], v[156:159], v[198:201], v[48:51]
	v_mfma_f32_16x16x32_bf16 v[36:39], v[148:151], v[206:209], v[36:39]
	v_mfma_f32_16x16x32_bf16 v[32:35], v[156:159], v[206:209], v[32:35]
	v_mfma_f32_16x16x32_bf16 v[20:23], v[148:151], v[222:225], v[20:23]
	v_mfma_f32_16x16x32_bf16 v[16:19], v[156:159], v[222:225], v[16:19]
	s_setprio 0
	s_setprio 1
	v_mfma_f32_16x16x32_bf16 v[44:47], v[170:173], v[186:189], v[44:47]
	v_mfma_f32_16x16x32_bf16 v[40:43], v[178:181], v[186:189], v[40:43]
	v_mfma_f32_16x16x32_bf16 v[28:31], v[170:173], v[194:197], v[28:31]
	v_mfma_f32_16x16x32_bf16 v[24:27], v[178:181], v[194:197], v[24:27]
	v_mfma_f32_16x16x32_bf16 v[12:15], v[170:173], v[202:205], v[12:15]
	v_mfma_f32_16x16x32_bf16 v[8:11], v[178:181], v[202:205], v[8:11]
	v_mfma_f32_16x16x32_bf16 v[4:7], v[170:173], v[210:213], v[4:7]
	v_mfma_f32_16x16x32_bf16 v[0:3], v[178:181], v[210:213], v[0:3]
	v_mfma_f32_16x16x32_bf16 v[44:47], v[174:177], v[190:193], v[44:47]
	v_mfma_f32_16x16x32_bf16 v[40:43], v[182:185], v[190:193], v[40:43]
	v_mfma_f32_16x16x32_bf16 v[28:31], v[174:177], v[198:201], v[28:31]
	v_mfma_f32_16x16x32_bf16 v[24:27], v[182:185], v[198:201], v[24:27]
	v_mfma_f32_16x16x32_bf16 v[12:15], v[174:177], v[206:209], v[12:15]
	v_mfma_f32_16x16x32_bf16 v[8:11], v[182:185], v[206:209], v[8:11]
	v_mfma_f32_16x16x32_bf16 v[4:7], v[174:177], v[222:225], v[4:7]
	v_mfma_f32_16x16x32_bf16 v[0:3], v[182:185], v[222:225], v[0:3]
	s_setprio 0
	s_barrier
	s_add_i32 s88, s88, 2
	s_add_u32 s38, s38, 0x100
	s_addc_u32 s39, s39, 0
	s_add_u32 s86, s86, 0x100
	s_addc_u32 s87, s87, 0
	s_cmp_gt_u32 s88, 13
